# scan units: XOR-swizzled al/bl gate rows (removes 8-way LDS bank conflict of the per-token row stores)
# speedup vs baseline: 1.0155x; 1.0142x over previous
; template <int DIR>
; __device__ __forceinline__ void rnn_scan_unit(const Params& p, LAS unsigned char* lds, int b, int g) {
;     ...
; #pragma unroll 1
;     for (int ci = 0; ci < NCH; ++ci) {
;         const int ck = DIR == 0 ? ci : NCH - 1 - ci, t0 = 128 * ck + 16 * wid;
; #pragma unroll
;         for (int i = 0; i < 3; ++i) { const int idx = lane + 64 * i; if (idx < 152) *(LAS u32x4*)(xrb + idx * 8) = xw[i]; }
;         asm volatile("s_waitcnt lgkmcnt(0)" ::: "memory");
;         if (ci + 1 < NCH) XR_LOAD(DIR == 0 ? ci + 1 : NCH - 2 - ci);
;         { const int tl0 = lane >> 3, c8 = lane & 7;
; #pragma unroll
;           for (int hh = 0; hh < 2; ++hh) { const int tl = tl0 + 8 * hh;
;               f32x4 o0 = cbv[0], o1 = cbv[1];
; #pragma unroll
;               for (int j = 0; j < 4; ++j) { const u32x4 xw_ = *(const LAS u32x4*)(xrb + (tl + j) * 64 + 8 * c8);
;                   o0[0] += cwv[j][0][0] * bflo(xw_.x); o0[1] += cwv[j][0][1] * bfhi(xw_.x); o0[2] += cwv[j][0][2] * bflo(xw_.y); o0[3] += cwv[j][0][3] * bfhi(xw_.y);
;                   o1[0] += cwv[j][1][0] * bflo(xw_.z); o1[1] += cwv[j][1][1] * bfhi(xw_.z); o1[2] += cwv[j][1][2] * bflo(xw_.w); o1[3] += cwv[j][1][3] * bfhi(xw_.w); }
;               *(LAS f32x4*)(xcf + tl * XS + 8 * c8) = o0; *(LAS f32x4*)(xcf + tl * XS + 8 * c8 + 4) = o1; } }
;         asm volatile("s_waitcnt lgkmcnt(0)" ::: "memory");
;         { const int tt = fr; const bool valid = (t0 + tt) < TT;
;           bf16x8 af[2];
; #pragma unroll
;           for (int ks = 0; ks < 2; ++ks) { const f32x4 x0 = *(const LAS f32x4*)(xcf + tt * XS + 32 * ks + 8 * fq), x1 = *(const LAS f32x4*)(xcf + tt * XS + 32 * ks + 8 * fq + 4);
;               u32x4 w; w.x = cvt_pk(x0[0], x0[1]); w.y = cvt_pk(x0[2], x0[3]); w.z = cvt_pk(x1[0], x1[1]); w.w = cvt_pk(x1[2], x1[3]); af[ks] = __builtin_bit_cast(bf16x8, w); }
; #pragma unroll
;           for (int n = 0; n < 4; ++n) { const int c4 = 16 * n + 4 * fq;
;               f32x4 ra = *(const LAS f32x4*)(cst + c4), ia = *(const LAS f32x4*)(cst + 64 + c4);
; #pragma unroll
;               for (int ks = 0; ks < 2; ++ks) { ra = MFMA16(wreg[(0 * 4 + n) * 2 + ks], af[ks], ra); ia = MFMA16(wl[((1 * 4 + n) * 2 + ks) * 64 + lane], af[ks], ia); }
;               const f32x4 xv = *(const LAS f32x4*)(xcf + tt * XS + c4);
;               const f32x4 spv = *(const LAS f32x4*)(cst + 128 + c4);
;               f32x4 av, bv;
.LBB0_538:
	s_or_b64 exec, exec, s[0:1]
	s_movk_i32 s0, 0x3a80
	v_mul_lo_u32 v0, v89, s0
	v_bfe_u32 v91, v116, 4, 2
	v_add_u32_e32 v98, 0, v0
	s_movk_i32 s0, 0x110
	v_mad_u32_u24 v100, v92, s0, v98
	v_lshlrev_b32_e32 v101, 5, v91
	v_lshlrev_b32_e32 v91, 4, v91
	v_lshlrev_b32_e32 v102, 4, v92
	v_add_u32_e32 v128, v100, v91
	s_add_i32 s0, 0, 0x23400
	v_sub_u32_e32 v130, v128, v102
	v_or_b32_e32 v102, 64, v91
	v_add_u32_e32 v126, s0, v91
	v_add_u32_e32 v127, s33, v91
	v_add_u32_e32 v129, s79, v91
	v_add_u32_e32 v131, s0, v102
	v_add_u32_e32 v132, s33, v102
	v_add_u32_e32 v133, s79, v102
	v_or_b32_e32 v102, 0x80, v91
	v_or_b32_e32 v91, 0xc0, v91
	s_lshl_b32 s17, s34, 1
	v_add_u32_e32 v137, s0, v91
	v_add_u32_e32 v138, s33, v91
	v_add_u32_e32 v139, s79, v91
	v_lshl_or_b32 v91, v116, 2, v152
	s_add_u32 s68, s40, s17
	v_add_u32_e32 v123, v98, v90
	v_lshrrev_b32_e32 v0, 2, v122
	v_add_u32_e32 v134, s0, v102
	v_add_u32_e32 v155, v98, v91
	v_cmp_eq_u32_e64 s[0:1], 6, v89
	v_cmp_eq_u32_e64 s[2:3], 5, v89
	v_cmp_eq_u32_e64 s[4:5], 4, v89
	v_cmp_eq_u32_e64 s[8:9], 3, v89
	v_cmp_eq_u32_e64 s[10:11], 2, v89
	v_cmp_eq_u32_e64 s[12:13], 1, v89
	s_addc_u32 s69, s41, 0
	v_mov_b32_e32 v91, v1
	v_ashrrev_i32_e32 v89, 31, v88
	v_add_u32_e32 v99, v123, v90
	v_lshl_add_u64 v[118:119], s[68:69], 0, v[90:91]
	v_lshl_add_u64 v[90:91], v[0:1], 0, v[88:89]
	v_lshlrev_b64 v[90:91], 10, v[90:91]
	v_mad_i64_i32 v[90:91], s[16:17], s16, v153, v[90:91]
	v_lshlrev_b32_e32 v104, 6, v116
	v_add3_u32 v156, v3, v88, s95
	s_lshl_b32 s16, s72, 6
	v_and_b32_e32 v3, 3, v116
	v_lshlrev_b32_e32 v103, 8, v0
	v_and_b32_e32 v104, 0xc0, v104
	v_lshlrev_b32_e32 v125, 7, v94
	s_and_b32 s16, s16, 0x380
	v_lshlrev_b32_e32 v3, 5, v3
	v_add3_u32 v124, v98, v103, v104
	v_lshlrev_b32_e32 v96, 4, v96
	v_lshlrev_b32_e32 v97, 4, v97
	v_mul_u32_u24_e32 v103, 0x110, v94
	v_or_b32_e32 v104, 0x400, v125
	v_or3_b32 v90, v90, s16, v3
	s_movk_i32 s6, 0x800
	v_add_u32_e32 v135, s33, v102
	v_add_u32_e32 v136, s79, v102
	v_lshl_add_u32 v154, v122, 2, v98
	v_cmp_gt_u32_e64 s[14:15], 64, v116
	v_add3_u32 v157, v95, v88, s95
	v_add3_u32 v158, v94, v88, s95
	v_lshl_add_u64 v[120:121], s[96:97], 0, v[90:91]
	v_add3_u32 v159, v0, v88, s6
	v_add3_u32 v160, v88, v92, s6
	s_mov_b32 s19, 0
	v_add_u32_e32 v161, v98, v93
	v_add_u32_e32 v164, v98, v96
	v_add_u32_e32 v165, v98, v97
	v_add_u32_e32 v166, v99, v103
	v_add_u32_e32 v167, v123, v104
	v_add_u32_e32 v168, v100, v101
	s_mov_b32 s34, 0
	s_waitcnt vmcnt(0)
	v_and_b32_e32 v228, 63, v163
	v_lshrrev_b32_e32 v229, 6, v163
	v_mul_u32_u24_e32 v229, 0x3a80, v229
	v_and_b32_e32 v230, 15, v163
	v_bfe_u32 v231, v163, 4, 2
	v_and_b32_e32 v232, 7, v230
	v_lshlrev_b32_e32 v232, 4, v232
	v_lshlrev_b32_e32 v233, 4, v231
	v_lshl_add_u32 v230, v230, 8, v229
	v_or_b32_e32 v224, 0, v233
	v_xor_b32_e32 v224, v224, v232
	v_add_u32_e32 v224, v224, v230
	v_or_b32_e32 v225, 64, v233
	v_xor_b32_e32 v225, v225, v232
	v_add_u32_e32 v225, v225, v230
	v_or_b32_e32 v226, 128, v233
	v_xor_b32_e32 v226, v226, v232
	v_add_u32_e32 v226, v226, v230
	v_or_b32_e32 v227, 192, v233
	v_xor_b32_e32 v227, v227, v232
	v_add_u32_e32 v227, v227, v230
	v_lshlrev_b32_e32 v233, 2, v228
	v_add_u32_e32 v230, 0x80, v229
	v_xor_b32_e32 v212, 0, v233
	v_add_u32_e32 v212, v212, v230
	v_xor_b32_e32 v213, 16, v233
	v_add_u32_e32 v213, v213, v230
	v_xor_b32_e32 v214, 32, v233
	v_add_u32_e32 v214, v214, v230
	v_xor_b32_e32 v215, 48, v233
	v_add_u32_e32 v215, v215, v230
	v_xor_b32_e32 v216, 64, v233
	v_add_u32_e32 v216, v216, v230
	v_xor_b32_e32 v217, 80, v233
	v_add_u32_e32 v217, v217, v230
	v_xor_b32_e32 v218, 96, v233
	v_add_u32_e32 v218, v218, v230
	v_xor_b32_e32 v219, 112, v233
	v_add_u32_e32 v219, v219, v230
	v_lshrrev_b32_e32 v230, 2, v228
	v_and_b32_e32 v231, 3, v228
	v_lshlrev_b32_e32 v231, 6, v231
	v_and_b32_e32 v232, 7, v230
	v_lshlrev_b32_e32 v232, 4, v232
	v_lshl_add_u32 v230, v230, 8, v229
	v_or_b32_e32 v220, 0, v231
	v_xor_b32_e32 v220, v220, v232
	v_add_u32_e32 v220, v220, v230
	v_or_b32_e32 v221, 16, v231
	v_xor_b32_e32 v221, v221, v232
	v_add_u32_e32 v221, v221, v230
	v_or_b32_e32 v222, 32, v231
	v_xor_b32_e32 v222, v222, v232
	v_add_u32_e32 v222, v222, v230
	v_or_b32_e32 v223, 48, v231
	v_xor_b32_e32 v223, v223, v232
	v_add_u32_e32 v223, v223, v230
	s_branch .LBB0_540

; #define LAS __attribute__((address_space(3)))
; #define MFMA16(a, b, c) __builtin_amdgcn_mfma_f32_16x16x32_bf16((a), (b), (c), 0, 0, 0)
; template <int DIR>
; __device__ __forceinline__ void rnn_scan_unit(const Params& p, LAS unsigned char* lds, int b, int g) {
;     ...
;           for (int n = 0; n < 4; ++n) { const int c4 = 16 * n + 4 * fq;
;               f32x4 ra = *(const LAS f32x4*)(cst + c4), ia = *(const LAS f32x4*)(cst + 64 + c4);
; #pragma unroll
;               for (int ks = 0; ks < 2; ++ks) { ra = MFMA16(wreg[(0 * 4 + n) * 2 + ks], af[ks], ra); ia = MFMA16(wl[((1 * 4 + n) * 2 + ks) * 64 + lane], af[ks], ia); }
;               const f32x4 xv = *(const LAS f32x4*)(xcf + tt * XS + c4);
;               const f32x4 spv = *(const LAS f32x4*)(cst + 128 + c4);
;               f32x4 av, bv;
; #pragma unroll
;               for (int i = 0; i < 4; ++i) { const float r = __builtin_amdgcn_rcpf(1.0f + __builtin_amdgcn_exp2f(ra[i])), ig = __builtin_amdgcn_rcpf(1.0f + __builtin_amdgcn_exp2f(ia[i]));
;                   const float a = __builtin_amdgcn_exp2f(r * spv[i]); const float em = fmaf(-a, a, 1.0f);
;                   av[i] = valid ? a : 1.0f; bv[i] = valid ? __builtin_amdgcn_sqrtf(fmaxf(em, 0.0f)) * ig * xv[i] : 0.0f; }
;               *(LAS f32x4*)(al + tt * 64 + c4) = av; *(LAS f32x4*)(bl + tt * 64 + c4) = bv; } }
.Lgate_nomask_7:
	ds_write_b128 v224, v[104:107] offset:6784
	ds_write_b128 v224, v[112:115] offset:10880
	ds_read_b128 v[96:99], v131
	ds_read_b128 v[100:103], v132
	ds_read_b128 v[104:107], v117 offset:10240
	s_waitcnt lgkmcnt(2)
	v_mfma_f32_16x16x32_bf16 v[96:99], v[52:55], v[88:91], v[96:99]
	v_mov_b32_e32 v113, 0
	v_mov_b32_e32 v112, 0
	s_waitcnt lgkmcnt(0)
	v_mfma_f32_16x16x32_bf16 v[100:103], v[104:107], v[88:91], v[100:103]
	v_mfma_f32_16x16x32_bf16 v[104:107], v[56:59], v[92:95], v[96:99]
	s_nop 2
	ds_read_b128 v[96:99], v117 offset:11264
	s_waitcnt lgkmcnt(0)
	v_mfma_f32_16x16x32_bf16 v[96:99], v[96:99], v[92:95], v[100:103]
	s_nop 1
	ds_read_b128 v[100:103], v128 offset:2496
	ds_read_b128 v[108:111], v133
	v_exp_f32_e32 v104, v104
	v_exp_f32_e32 v105, v105
	v_exp_f32_e32 v106, v106
	v_exp_f32_e32 v107, v107
	v_exp_f32_e32 v96, v96
	v_exp_f32_e32 v97, v97
	v_exp_f32_e32 v98, v98
	v_exp_f32_e32 v99, v99
	v_add_f32_e32 v104, 1.0, v104
	v_add_f32_e32 v105, 1.0, v105
	v_add_f32_e32 v106, 1.0, v106
	v_add_f32_e32 v107, 1.0, v107
	v_add_f32_e32 v96, 1.0, v96
	v_add_f32_e32 v97, 1.0, v97
	v_add_f32_e32 v98, 1.0, v98
	v_add_f32_e32 v99, 1.0, v99
	v_rcp_f32_e32 v104, v104
	v_rcp_f32_e32 v105, v105
	v_rcp_f32_e32 v106, v106
	v_rcp_f32_e32 v107, v107
	v_rcp_f32_e32 v96, v96
	v_rcp_f32_e32 v97, v97
	v_rcp_f32_e32 v98, v98
	v_rcp_f32_e32 v99, v99
	s_waitcnt lgkmcnt(0)
	v_mul_f32_e32 v104, v104, v108
	v_mul_f32_e32 v105, v105, v109
	v_mul_f32_e32 v106, v106, v110
	v_mul_f32_e32 v107, v107, v111
	v_exp_f32_e32 v104, v104
	v_exp_f32_e32 v105, v105
	v_exp_f32_e32 v106, v106
	v_exp_f32_e32 v107, v107
	v_fma_f32 v112, -v104, v104, 1.0
	v_fma_f32 v113, -v105, v105, 1.0
	v_fma_f32 v114, -v106, v106, 1.0
	v_fma_f32 v115, -v107, v107, 1.0
	v_max_f32_e32 v112, 0, v112
	v_max_f32_e32 v113, 0, v113
	v_max_f32_e32 v114, 0, v114
	v_max_f32_e32 v115, 0, v115
	v_sqrt_f32_e32 v112, v112
	v_sqrt_f32_e32 v113, v113
	v_sqrt_f32_e32 v114, v114
	v_sqrt_f32_e32 v115, v115
	v_mul_f32_e32 v96, v96, v112
	v_mul_f32_e32 v97, v97, v113
	v_mul_f32_e32 v98, v98, v114
	v_mul_f32_e32 v99, v99, v115
	v_mul_f32_e32 v112, v100, v96
	v_mul_f32_e32 v113, v101, v97
	v_mul_f32_e32 v114, v102, v98
	v_mul_f32_e32 v115, v103, v99
	s_cmp_eq_u64 s[16:17], exec
	s_cbranch_scc1 .Lgate_nomask_6
	v_cndmask_b32_e64 v112, 0, v112, s[16:17]
	v_cndmask_b32_e64 v113, 0, v113, s[16:17]
	v_cndmask_b32_e64 v114, 0, v114, s[16:17]
	v_cndmask_b32_e64 v115, 0, v115, s[16:17]
	v_cndmask_b32_e64 v104, 1.0, v104, s[16:17]
	v_cndmask_b32_e64 v105, 1.0, v105, s[16:17]
	v_cndmask_b32_e64 v106, 1.0, v106, s[16:17]
	v_cndmask_b32_e64 v107, 1.0, v107, s[16:17]
.Lgate_nomask_6:
	ds_write_b128 v225, v[104:107] offset:6784
	ds_write_b128 v225, v[112:115] offset:10880
	ds_read_b128 v[96:99], v134
	ds_read_b128 v[100:103], v135
	ds_read_b128 v[104:107], v117 offset:12288
	s_waitcnt lgkmcnt(2)
	v_mfma_f32_16x16x32_bf16 v[96:99], v[60:63], v[88:91], v[96:99]
	v_mov_b32_e32 v113, 0
	v_mov_b32_e32 v112, 0
	s_waitcnt lgkmcnt(0)
	v_mfma_f32_16x16x32_bf16 v[100:103], v[104:107], v[88:91], v[100:103]
	v_mfma_f32_16x16x32_bf16 v[104:107], v[64:67], v[92:95], v[96:99]
	s_nop 2
	ds_read_b128 v[96:99], v117 offset:13312
	s_waitcnt lgkmcnt(0)
	v_mfma_f32_16x16x32_bf16 v[96:99], v[96:99], v[92:95], v[100:103]
	s_nop 1
	ds_read_b128 v[100:103], v128 offset:2560
	ds_read_b128 v[108:111], v136
	v_exp_f32_e32 v104, v104
	v_exp_f32_e32 v105, v105
	v_exp_f32_e32 v106, v106
	v_exp_f32_e32 v107, v107
	v_exp_f32_e32 v96, v96
	v_exp_f32_e32 v97, v97
	v_exp_f32_e32 v98, v98
	v_exp_f32_e32 v99, v99
	v_add_f32_e32 v104, 1.0, v104
	v_add_f32_e32 v105, 1.0, v105
	v_add_f32_e32 v106, 1.0, v106
	v_add_f32_e32 v107, 1.0, v107
	v_add_f32_e32 v96, 1.0, v96
	v_add_f32_e32 v97, 1.0, v97
	v_add_f32_e32 v98, 1.0, v98
	v_add_f32_e32 v99, 1.0, v99
	v_rcp_f32_e32 v104, v104
	v_rcp_f32_e32 v105, v105
	v_rcp_f32_e32 v106, v106
	v_rcp_f32_e32 v107, v107
	v_rcp_f32_e32 v96, v96
	v_rcp_f32_e32 v97, v97
	v_rcp_f32_e32 v98, v98
	v_rcp_f32_e32 v99, v99
	s_waitcnt lgkmcnt(0)
	v_mul_f32_e32 v104, v104, v108
	v_mul_f32_e32 v105, v105, v109
	v_mul_f32_e32 v106, v106, v110
	v_mul_f32_e32 v107, v107, v111
	v_exp_f32_e32 v104, v104
	v_exp_f32_e32 v105, v105
	v_exp_f32_e32 v106, v106
	v_exp_f32_e32 v107, v107
	v_fma_f32 v112, -v104, v104, 1.0
	v_fma_f32 v113, -v105, v105, 1.0
	v_fma_f32 v114, -v106, v106, 1.0
	v_fma_f32 v115, -v107, v107, 1.0
	v_max_f32_e32 v112, 0, v112
	v_max_f32_e32 v113, 0, v113
	v_max_f32_e32 v114, 0, v114
	v_max_f32_e32 v115, 0, v115
	v_sqrt_f32_e32 v112, v112
	v_sqrt_f32_e32 v113, v113
	v_sqrt_f32_e32 v114, v114
	v_sqrt_f32_e32 v115, v115
	v_mul_f32_e32 v96, v96, v112
	v_mul_f32_e32 v97, v97, v113
	v_mul_f32_e32 v98, v98, v114
	v_mul_f32_e32 v99, v99, v115
	v_mul_f32_e32 v112, v100, v96
	v_mul_f32_e32 v113, v101, v97
	v_mul_f32_e32 v114, v102, v98
	v_mul_f32_e32 v115, v103, v99
	s_cmp_eq_u64 s[16:17], exec
	s_cbranch_scc1 .Lgate_nomask_5
	v_cndmask_b32_e64 v112, 0, v112, s[16:17]
	v_cndmask_b32_e64 v113, 0, v113, s[16:17]
	v_cndmask_b32_e64 v114, 0, v114, s[16:17]
	v_cndmask_b32_e64 v115, 0, v115, s[16:17]
	v_cndmask_b32_e64 v104, 1.0, v104, s[16:17]
	v_cndmask_b32_e64 v105, 1.0, v105, s[16:17]
	v_cndmask_b32_e64 v106, 1.0, v106, s[16:17]
	v_cndmask_b32_e64 v107, 1.0, v107, s[16:17]
; #define LAS __attribute__((address_space(3)))
; #define MFMA16(a, b, c) __builtin_amdgcn_mfma_f32_16x16x32_bf16((a), (b), (c), 0, 0, 0)
; template <int DIR>
; __device__ __forceinline__ void rnn_scan_unit(const Params& p, LAS unsigned char* lds, int b, int g) {
;     ...
;           for (int n = 0; n < 4; ++n) { const int c4 = 16 * n + 4 * fq;
;               f32x4 ra = *(const LAS f32x4*)(cst + c4), ia = *(const LAS f32x4*)(cst + 64 + c4);
; #pragma unroll
;               for (int ks = 0; ks < 2; ++ks) { ra = MFMA16(wreg[(0 * 4 + n) * 2 + ks], af[ks], ra); ia = MFMA16(wl[((1 * 4 + n) * 2 + ks) * 64 + lane], af[ks], ia); }
;               const f32x4 xv = *(const LAS f32x4*)(xcf + tt * XS + c4);
;               const f32x4 spv = *(const LAS f32x4*)(cst + 128 + c4);
;               f32x4 av, bv;
; #pragma unroll
;               for (int i = 0; i < 4; ++i) { const float r = __builtin_amdgcn_rcpf(1.0f + __builtin_amdgcn_exp2f(ra[i])), ig = __builtin_amdgcn_rcpf(1.0f + __builtin_amdgcn_exp2f(ia[i]));
;                   const float a = __builtin_amdgcn_exp2f(r * spv[i]); const float em = fmaf(-a, a, 1.0f);
;                   av[i] = valid ? a : 1.0f; bv[i] = valid ? __builtin_amdgcn_sqrtf(fmaxf(em, 0.0f)) * ig * xv[i] : 0.0f; }
;               *(LAS f32x4*)(al + tt * 64 + c4) = av; *(LAS f32x4*)(bl + tt * 64 + c4) = bv; } }
.Lgate_nomask_5:
	ds_write_b128 v226, v[104:107] offset:6784
	ds_write_b128 v226, v[112:115] offset:10880
	ds_read_b128 v[96:99], v137
	ds_read_b128 v[100:103], v138
	ds_read_b128 v[104:107], v117 offset:14336
	s_waitcnt lgkmcnt(2)
	v_mfma_f32_16x16x32_bf16 v[96:99], v[68:71], v[88:91], v[96:99]
	s_waitcnt lgkmcnt(0)
	v_mfma_f32_16x16x32_bf16 v[88:91], v[104:107], v[88:91], v[100:103]
	v_mov_b32_e32 v105, 0
	s_nop 1
	ds_read_b128 v[100:103], v117 offset:15360
	v_mov_b32_e32 v104, 0
	v_mfma_f32_16x16x32_bf16 v[96:99], v[72:75], v[92:95], v[96:99]
	s_waitcnt lgkmcnt(0)
	v_mfma_f32_16x16x32_bf16 v[88:91], v[100:103], v[92:95], v[88:91]
	ds_read_b128 v[92:95], v128 offset:2624
	ds_read_b128 v[100:103], v139
	s_nop 3
	v_exp_f32_e32 v96, v96
	v_exp_f32_e32 v97, v97
	v_exp_f32_e32 v98, v98
	v_exp_f32_e32 v99, v99
	v_exp_f32_e32 v88, v88
	v_exp_f32_e32 v89, v89
	v_exp_f32_e32 v90, v90
	v_exp_f32_e32 v91, v91
	v_add_f32_e32 v96, 1.0, v96
	v_add_f32_e32 v97, 1.0, v97
	v_add_f32_e32 v98, 1.0, v98
	v_add_f32_e32 v99, 1.0, v99
	v_add_f32_e32 v88, 1.0, v88
	v_add_f32_e32 v89, 1.0, v89
	v_add_f32_e32 v90, 1.0, v90
	v_add_f32_e32 v91, 1.0, v91
	v_rcp_f32_e32 v96, v96
	v_rcp_f32_e32 v97, v97
	v_rcp_f32_e32 v98, v98
	v_rcp_f32_e32 v99, v99
	v_rcp_f32_e32 v88, v88
	v_rcp_f32_e32 v89, v89
	v_rcp_f32_e32 v90, v90
	v_rcp_f32_e32 v91, v91
	s_waitcnt lgkmcnt(0)
	v_mul_f32_e32 v96, v96, v100
	v_mul_f32_e32 v97, v97, v101
	v_mul_f32_e32 v98, v98, v102
	v_mul_f32_e32 v99, v99, v103
	v_exp_f32_e32 v96, v96
	v_exp_f32_e32 v97, v97
	v_exp_f32_e32 v98, v98
	v_exp_f32_e32 v99, v99
	v_fma_f32 v104, -v96, v96, 1.0
	v_fma_f32 v105, -v97, v97, 1.0
	v_fma_f32 v106, -v98, v98, 1.0
	v_fma_f32 v107, -v99, v99, 1.0
	v_max_f32_e32 v104, 0, v104
	v_max_f32_e32 v105, 0, v105
	v_max_f32_e32 v106, 0, v106
	v_max_f32_e32 v107, 0, v107
	v_sqrt_f32_e32 v104, v104
	v_sqrt_f32_e32 v105, v105
	v_sqrt_f32_e32 v106, v106
	v_sqrt_f32_e32 v107, v107
	v_mul_f32_e32 v88, v88, v104
	v_mul_f32_e32 v89, v89, v105
	v_mul_f32_e32 v90, v90, v106
	v_mul_f32_e32 v91, v91, v107
	v_mul_f32_e32 v104, v92, v88
	v_mul_f32_e32 v105, v93, v89
	v_mul_f32_e32 v106, v94, v90
	v_mul_f32_e32 v107, v95, v91
	s_cmp_eq_u64 s[16:17], exec
	s_cbranch_scc1 .Lgate_nomask_4
	v_cndmask_b32_e64 v104, 0, v104, s[16:17]
	v_cndmask_b32_e64 v105, 0, v105, s[16:17]
	v_cndmask_b32_e64 v106, 0, v106, s[16:17]
	v_cndmask_b32_e64 v107, 0, v107, s[16:17]
	v_cndmask_b32_e64 v96, 1.0, v96, s[16:17]
	v_cndmask_b32_e64 v97, 1.0, v97, s[16:17]
	v_cndmask_b32_e64 v98, 1.0, v98, s[16:17]
	v_cndmask_b32_e64 v99, 1.0, v99, s[16:17]
; #define LAS __attribute__((address_space(3)))
; __device__ __forceinline__ unsigned cvt_pk(float lo, float hi) { unsigned r; asm("v_cvt_pk_bf16_f32 %0, %1, %2" : "=v"(r) : "v"(lo), "v"(hi)); return r; }
; #define LDS_BARRIER() asm volatile("s_waitcnt lgkmcnt(0)\n\ts_barrier" ::: "memory")
; template <int DIR>
; __device__ __forceinline__ void rnn_scan_unit(const Params& p, LAS unsigned char* lds, int b, int g) {
;     ...
;               *(LAS f32x4*)(al + tt * 64 + c4) = av; *(LAS f32x4*)(bl + tt * 64 + c4) = bv; } }
;         asm volatile("s_waitcnt lgkmcnt(0)" ::: "memory");
;         LAS float* sgA = sg + (ci & 1) * 1024; LAS float* sgB = sgA + 512;
;         float av_[16], bv_[16];
;         { float A = 1.f, B = 0.f;
; #pragma unroll
;           for (int k = 0; k < 16; ++k) { const int tt = DIR == 0 ? k : 15 - k; av_[k] = al[tt * 64 + ch]; bv_[k] = bl[tt * 64 + ch]; B = av_[k] * B + bv_[k]; A *= av_[k]; }
;           sgA[seg * 64 + ch] = A; sgB[seg * 64 + ch] = B; }
;         LDS_BARRIER();
;         float h = hcar, hin = hcar;
; #pragma unroll
;         for (int s = 0; s < 8; ++s) { const int sx = DIR == 0 ? s : 7 - s; hin = (sx == seg) ? h : hin; h = sgA[sx * 64 + ch] * h + sgB[sx * 64 + ch]; }
;         hcar = h;
; #pragma unroll
;         for (int k = 0; k < 16; ++k) { const int tt = DIR == 0 ? k : 15 - k; hin = av_[k] * hin + bv_[k]; bl[tt * 64 + ch] = hin; }
;         asm volatile("s_waitcnt lgkmcnt(0)" ::: "memory");
;         { const int tk = lane >> 2, cq4 = lane & 3;
;           if (t0 + tk < TT) { const LAS float* src = bl + tk * 64 + 16 * cq4;
;               const f32x4 x0 = *(const LAS f32x4*)(src), x1 = *(const LAS f32x4*)(src + 4), x2 = *(const LAS f32x4*)(src + 8), x3 = *(const LAS f32x4*)(src + 12);
;               u32x4 w0, w1; w0.x = cvt_pk(x0[0], x0[1]); w0.y = cvt_pk(x0[2], x0[3]); w0.z = cvt_pk(x1[0], x1[1]); w0.w = cvt_pk(x1[2], x1[3]);
;               w1.x = cvt_pk(x2[0], x2[1]); w1.y = cvt_pk(x2[2], x2[3]); w1.z = cvt_pk(x3[0], x3[1]); w1.w = cvt_pk(x3[2], x3[3]);
;               bf16_t* hp = H + ((size_t)b * TT + t0 + tk) * 512 + 64 * g + 16 * cq4;
;               *(u32x4*)hp = w0; *(u32x4*)(hp + 8) = w1; } }
.Lgate_nomask_4:
	ds_write_b128 v227, v[96:99] offset:6784
	ds_write_b128 v227, v[104:107] offset:10880
	s_waitcnt lgkmcnt(0)
	ds_read2st64_b32 v[194:195], v219 offset0:33 offset1:41
	ds_read2st64_b32 v[210:211], v219 offset0:49 offset1:57
	ds_read2st64_b32 v[192:193], v218 offset0:32 offset1:40
	ds_read2st64_b32 v[208:209], v218 offset0:48 offset1:56
	ds_read2st64_b32 v[190:191], v217 offset0:31 offset1:39
	ds_read2st64_b32 v[206:207], v217 offset0:47 offset1:55
	ds_read2st64_b32 v[188:189], v216 offset0:30 offset1:38
	ds_read2st64_b32 v[204:205], v216 offset0:46 offset1:54
	ds_read2st64_b32 v[186:187], v215 offset0:29 offset1:37
	ds_read2st64_b32 v[202:203], v215 offset0:45 offset1:53
	ds_read2st64_b32 v[184:185], v214 offset0:28 offset1:36
	ds_read2st64_b32 v[200:201], v214 offset0:44 offset1:52
	ds_read2st64_b32 v[182:183], v213 offset0:27 offset1:35
	ds_read2st64_b32 v[198:199], v213 offset0:43 offset1:51
	ds_read2st64_b32 v[180:181], v212 offset0:26 offset1:34
	ds_read2st64_b32 v[196:197], v212 offset0:42 offset1:50
	s_and_b32 s16, s34, 0x400
	s_lshl_b32 s16, s16, 2
	s_add_i32 s16, s16, 0
	s_add_i32 s16, s16, 0x1d400
	v_lshl_add_u32 v110, v116, 2, s16
	s_waitcnt lgkmcnt(14)
	v_fma_f32 v0, 0, v195, v211
	s_waitcnt lgkmcnt(12)
	v_fma_f32 v0, v0, v193, v209
	v_mul_f32_e32 v3, v195, v193
	s_waitcnt lgkmcnt(10)
	v_fma_f32 v0, v0, v191, v207
	v_mul_f32_e32 v3, v3, v191
	s_waitcnt lgkmcnt(8)
	v_fma_f32 v0, v0, v189, v205
	v_mul_f32_e32 v3, v3, v189
	s_waitcnt lgkmcnt(6)
	v_fma_f32 v0, v0, v187, v203
	v_mul_f32_e32 v3, v3, v187
	s_waitcnt lgkmcnt(4)
	v_fma_f32 v0, v0, v185, v201
	v_mul_f32_e32 v3, v3, v185
	s_waitcnt lgkmcnt(2)
	v_fma_f32 v0, v0, v183, v199
	v_mul_f32_e32 v3, v3, v183
	s_waitcnt lgkmcnt(0)
	v_fma_f32 v0, v0, v181, v197
	v_mul_f32_e32 v3, v3, v181
	v_fma_f32 v0, v0, v194, v210
	v_mul_f32_e32 v3, v3, v194
	v_fma_f32 v0, v0, v192, v208
	v_mul_f32_e32 v3, v3, v192
	v_fma_f32 v0, v0, v190, v206
	v_mul_f32_e32 v3, v3, v190
	v_fma_f32 v0, v0, v188, v204
	v_mul_f32_e32 v3, v3, v188
	v_fma_f32 v0, v0, v186, v202
	v_mul_f32_e32 v3, v3, v186
	v_fma_f32 v0, v0, v184, v200
	v_mul_f32_e32 v3, v3, v184
	v_fma_f32 v0, v0, v182, v198
	v_mul_f32_e32 v3, v3, v182
	v_fma_f32 v0, v0, v180, v196
	v_mul_f32_e32 v3, v3, v180
	ds_write2st64_b32 v110, v3, v0 offset1:8
	s_waitcnt lgkmcnt(0)
	s_barrier
	v_lshl_add_u32 v0, v122, 2, s16
	ds_read2st64_b32 v[110:111], v0 offset0:6 offset1:7
	ds_read2st64_b32 v[176:177], v0 offset0:14 offset1:15
	s_waitcnt lgkmcnt(0)
	v_fma_f32 v3, v2, v111, v177
	v_cndmask_b32_e64 v2, v2, v3, s[0:1]
	v_fmac_f32_e32 v176, v3, v110
	v_cndmask_b32_e64 v177, v2, v176, s[2:3]
	ds_read2st64_b32 v[2:3], v0 offset0:4 offset1:5
	ds_read2st64_b32 v[110:111], v0 offset0:12 offset1:13
	s_waitcnt lgkmcnt(0)
	v_fma_f32 v3, v176, v3, v111
	v_cndmask_b32_e64 v111, v177, v3, s[4:5]
	v_fmac_f32_e32 v110, v3, v2
	ds_read2st64_b32 v[2:3], v0 offset0:2 offset1:3
	ds_read2st64_b32 v[176:177], v0 offset0:10 offset1:11
	v_cndmask_b32_e64 v111, v111, v110, s[8:9]
	s_waitcnt lgkmcnt(0)
	v_fma_f32 v3, v110, v3, v177
	v_cndmask_b32_e64 v110, v111, v3, s[10:11]
	v_fmac_f32_e32 v176, v3, v2
	v_cndmask_b32_e64 v177, v110, v176, s[12:13]
	ds_read2st64_b32 v[110:111], v0 offset1:1
	ds_read2st64_b32 v[2:3], v0 offset0:8 offset1:9
	s_waitcnt lgkmcnt(0)
	v_fma_f32 v0, v176, v111, v3
	v_cndmask_b32_e64 v3, v177, v0, s[14:15]
	v_fma_f32 v211, v195, v3, v211
	v_fma_f32 v209, v193, v211, v209
	v_fma_f32 v207, v191, v209, v207
	v_fma_f32 v205, v189, v207, v205
	v_fma_f32 v203, v187, v205, v203
	v_fma_f32 v201, v185, v203, v201
	v_fma_f32 v199, v183, v201, v199
	v_fma_f32 v197, v181, v199, v197
	v_fma_f32 v210, v194, v197, v210
	ds_write2st64_b32 v219, v210, v211 offset0:49 offset1:57
	v_fma_f32 v208, v192, v210, v208
	ds_write2st64_b32 v218, v208, v209 offset0:48 offset1:56
	v_fma_f32 v206, v190, v208, v206
	ds_write2st64_b32 v217, v206, v207 offset0:47 offset1:55
	v_fma_f32 v204, v188, v206, v204
	ds_write2st64_b32 v216, v204, v205 offset0:46 offset1:54
	v_fma_f32 v202, v186, v204, v202
	ds_write2st64_b32 v215, v202, v203 offset0:45 offset1:53
	v_fma_f32 v200, v184, v202, v200
	ds_write2st64_b32 v214, v200, v201 offset0:44 offset1:52
	v_fma_f32 v198, v182, v200, v198
	ds_write2st64_b32 v213, v198, v199 offset0:43 offset1:51
	v_fma_f32 v196, v180, v198, v196
	ds_write2st64_b32 v212, v196, v197 offset0:42 offset1:50
	s_waitcnt lgkmcnt(0)
	v_add_u32_e32 v3, s19, v159
	v_cmp_gt_i32_e64 s[16:17], s86, v3
	s_waitcnt vmcnt(0)
	s_and_saveexec_b64 s[76:77], s[16:17]
	s_cbranch_execz .LBB0_539
	ds_read_b128 v[88:91], v220 offset:10880
	ds_read_b128 v[92:95], v221 offset:10880
	ds_read_b128 v[96:99], v222 offset:10880
	ds_read_b128 v[100:103], v223 offset:10880
	s_waitcnt lgkmcnt(3)
	v_cvt_pk_bf16_f32 v88, v88, v89
	v_cvt_pk_bf16_f32 v89, v90, v91
	s_waitcnt lgkmcnt(2)
	v_cvt_pk_bf16_f32 v90, v92, v93
	v_cvt_pk_bf16_f32 v91, v94, v95
	s_waitcnt lgkmcnt(1)
	v_cvt_pk_bf16_f32 v92, v96, v97
	v_cvt_pk_bf16_f32 v93, v98, v99
	s_waitcnt lgkmcnt(0)
	v_cvt_pk_bf16_f32 v94, v100, v101
	v_cvt_pk_bf16_f32 v95, v102, v103
	global_store_dwordx4 v[120:121], v[88:91], off
	global_store_dwordx4 v[120:121], v[92:95], off offset:16
	s_branch .LBB0_539

; template <int DIR>
; __device__ __forceinline__ void rnn_scan_unit(const Params& p, LAS unsigned char* lds, int b, int g) {
;     ...
; #pragma unroll 1
;     for (int ci = 0; ci < NCH; ++ci) {
;         const int ck = DIR == 0 ? ci : NCH - 1 - ci, t0 = 128 * ck + 16 * wid;
; #pragma unroll
;         for (int i = 0; i < 3; ++i) { const int idx = lane + 64 * i; if (idx < 152) *(LAS u32x4*)(xrb + idx * 8) = xw[i]; }
;         asm volatile("s_waitcnt lgkmcnt(0)" ::: "memory");
;         if (ci + 1 < NCH) XR_LOAD(DIR == 0 ? ci + 1 : NCH - 2 - ci);
;         { const int tl0 = lane >> 3, c8 = lane & 7;
; #pragma unroll
;           for (int hh = 0; hh < 2; ++hh) { const int tl = tl0 + 8 * hh;
;               f32x4 o0 = cbv[0], o1 = cbv[1];
; #pragma unroll
;               for (int j = 0; j < 4; ++j) { const u32x4 xw_ = *(const LAS u32x4*)(xrb + (tl + j) * 64 + 8 * c8);
;                   o0[0] += cwv[j][0][0] * bflo(xw_.x); o0[1] += cwv[j][0][1] * bfhi(xw_.x); o0[2] += cwv[j][0][2] * bflo(xw_.y); o0[3] += cwv[j][0][3] * bfhi(xw_.y);
;                   o1[0] += cwv[j][1][0] * bflo(xw_.z); o1[1] += cwv[j][1][1] * bfhi(xw_.z); o1[2] += cwv[j][1][2] * bflo(xw_.w); o1[3] += cwv[j][1][3] * bfhi(xw_.w); }
;               *(LAS f32x4*)(xcf + tl * XS + 8 * c8) = o0; *(LAS f32x4*)(xcf + tl * XS + 8 * c8 + 4) = o1; } }
;         asm volatile("s_waitcnt lgkmcnt(0)" ::: "memory");
;         { const int tt = fr; const bool valid = (t0 + tt) < TT;
;           bf16x8 af[2];
; #pragma unroll
;           for (int ks = 0; ks < 2; ++ks) { const f32x4 x0 = *(const LAS f32x4*)(xcf + tt * XS + 32 * ks + 8 * fq), x1 = *(const LAS f32x4*)(xcf + tt * XS + 32 * ks + 8 * fq + 4);
;               u32x4 w; w.x = cvt_pk(x0[0], x0[1]); w.y = cvt_pk(x0[2], x0[3]); w.z = cvt_pk(x1[0], x1[1]); w.w = cvt_pk(x1[2], x1[3]); af[ks] = __builtin_bit_cast(bf16x8, w); }
; #pragma unroll
;           for (int n = 0; n < 4; ++n) { const int c4 = 16 * n + 4 * fq;
;               f32x4 ra = *(const LAS f32x4*)(cst + c4), ia = *(const LAS f32x4*)(cst + 64 + c4);
; #pragma unroll
;               for (int ks = 0; ks < 2; ++ks) { ra = MFMA16(wreg[(0 * 4 + n) * 2 + ks], af[ks], ra); ia = MFMA16(wl[((1 * 4 + n) * 2 + ks) * 64 + lane], af[ks], ia); }
;               const f32x4 xv = *(const LAS f32x4*)(xcf + tt * XS + c4);
;               const f32x4 spv = *(const LAS f32x4*)(cst + 128 + c4);
;               f32x4 av, bv;
.LBB0_594:
	s_or_b64 exec, exec, s[0:1]
	s_movk_i32 s0, 0x3a80
	v_mul_lo_u32 v0, v89, s0
	v_bfe_u32 v91, v120, 4, 2
	v_add_u32_e32 v98, 0, v0
	s_movk_i32 s0, 0x110
	v_mad_u32_u24 v100, v92, s0, v98
	v_lshlrev_b32_e32 v101, 5, v91
	v_lshlrev_b32_e32 v91, 4, v91
	v_lshlrev_b32_e32 v102, 4, v92
	v_add_u32_e32 v129, v100, v91
	s_add_i32 s0, 0, 0x23400
	v_sub_u32_e32 v131, v129, v102
	v_or_b32_e32 v102, 64, v91
	s_lshl_b32 s16, s16, 1
	v_add_u32_e32 v127, s0, v91
	v_add_u32_e32 v128, s33, v91
	v_add_u32_e32 v130, s79, v91
	v_add_u32_e32 v132, s0, v102
	v_add_u32_e32 v133, s33, v102
	v_add_u32_e32 v134, s79, v102
	v_or_b32_e32 v102, 0x80, v91
	v_or_b32_e32 v91, 0xc0, v91
	s_add_u32 s16, s40, s16
	v_add_u32_e32 v123, v98, v90
	v_lshrrev_b32_e32 v0, 2, v121
	v_add_u32_e32 v138, s0, v91
	v_add_u32_e32 v139, s33, v91
	v_add_u32_e32 v154, s79, v91
	s_addc_u32 s17, s41, 0
	v_mov_b32_e32 v91, v1
	v_add_u32_e32 v99, v123, v90
	v_add_u32_e32 v135, s0, v102
	v_cmp_eq_u32_e64 s[0:1], 1, v89
	v_cmp_eq_u32_e64 s[2:3], 2, v89
	v_cmp_eq_u32_e64 s[4:5], 3, v89
	v_cmp_eq_u32_e64 s[8:9], 4, v89
	v_cmp_eq_u32_e64 s[10:11], 5, v89
	v_cmp_eq_u32_e64 s[12:13], 6, v89
	v_cmp_eq_u32_e64 s[14:15], 7, v89
	v_lshl_add_u64 v[116:117], s[16:17], 0, v[90:91]
	v_lshl_add_u64 v[90:91], v[0:1], 0, s[74:75]
	v_ashrrev_i32_e32 v89, 31, v88
	v_lshlrev_b32_e32 v104, 6, v120
	v_add3_u32 v155, v2, v88, s70
	v_lshl_add_u64 v[90:91], v[90:91], 0, v[88:89]
	s_lshl_b32 s16, s72, 6
	v_and_b32_e32 v2, 3, v120
	v_lshlrev_b32_e32 v103, 8, v0
	v_and_b32_e32 v104, 0xc0, v104
	v_lshlrev_b32_e32 v126, 7, v94
	v_lshlrev_b64 v[90:91], 10, v[90:91]
	s_and_b32 s16, s16, 0x380
	v_lshlrev_b32_e32 v2, 5, v2
	v_add3_u32 v125, v98, v103, v104
	v_lshlrev_b32_e32 v96, 4, v96
	v_lshlrev_b32_e32 v97, 4, v97
	v_mul_u32_u24_e32 v103, 0x110, v94
	v_or_b32_e32 v104, 0x400, v126
	v_or3_b32 v90, v90, s16, v2
	v_lshl_add_u32 v124, v121, 2, v98
	v_add_u32_e32 v136, s33, v102
	v_add_u32_e32 v137, s79, v102
	v_add3_u32 v156, v95, v88, s70
	v_add3_u32 v157, v94, v88, s70
	v_lshl_add_u64 v[118:119], s[80:81], 0, v[90:91]
	v_add_u32_e32 v158, v0, v88
	v_add_u32_e32 v159, v88, v92
	s_mov_b32 s19, 0
	v_add_u32_e32 v160, v98, v93
	v_add_u32_e32 v161, v98, v96
	v_add_u32_e32 v164, v98, v97
	v_add_u32_e32 v165, v99, v103
	v_add_u32_e32 v166, v123, v104
	v_add_u32_e32 v167, v100, v101
	s_mov_b32 s34, 0
	s_waitcnt vmcnt(0)
	v_and_b32_e32 v228, 63, v163
	v_lshrrev_b32_e32 v229, 6, v163
	v_mul_u32_u24_e32 v229, 0x3a80, v229
	v_and_b32_e32 v230, 15, v163
	v_bfe_u32 v231, v163, 4, 2
	v_and_b32_e32 v232, 7, v230
	v_lshlrev_b32_e32 v232, 4, v232
	v_lshlrev_b32_e32 v233, 4, v231
	v_lshl_add_u32 v230, v230, 8, v229
	v_or_b32_e32 v224, 0, v233
	v_xor_b32_e32 v224, v224, v232
	v_add_u32_e32 v224, v224, v230
	v_or_b32_e32 v225, 64, v233
	v_xor_b32_e32 v225, v225, v232
	v_add_u32_e32 v225, v225, v230
	v_or_b32_e32 v226, 128, v233
	v_xor_b32_e32 v226, v226, v232
	v_add_u32_e32 v226, v226, v230
	v_or_b32_e32 v227, 192, v233
	v_xor_b32_e32 v227, v227, v232
	v_add_u32_e32 v227, v227, v230
	v_lshlrev_b32_e32 v233, 2, v228
	v_add_u32_e32 v230, 0x80, v229
	v_xor_b32_e32 v212, 0, v233
	v_add_u32_e32 v212, v212, v230
	v_xor_b32_e32 v213, 16, v233
	v_add_u32_e32 v213, v213, v230
	v_xor_b32_e32 v214, 32, v233
	v_add_u32_e32 v214, v214, v230
	v_xor_b32_e32 v215, 48, v233
	v_add_u32_e32 v215, v215, v230
	v_xor_b32_e32 v216, 64, v233
	v_add_u32_e32 v216, v216, v230
	v_xor_b32_e32 v217, 80, v233
	v_add_u32_e32 v217, v217, v230
	v_xor_b32_e32 v218, 96, v233
	v_add_u32_e32 v218, v218, v230
	v_xor_b32_e32 v219, 112, v233
	v_add_u32_e32 v219, v219, v230
	v_lshrrev_b32_e32 v230, 2, v228
	v_and_b32_e32 v231, 3, v228
	v_lshlrev_b32_e32 v231, 6, v231
	v_and_b32_e32 v232, 7, v230
	v_lshlrev_b32_e32 v232, 4, v232
	v_lshl_add_u32 v230, v230, 8, v229
	v_or_b32_e32 v220, 0, v231
	v_xor_b32_e32 v220, v220, v232
	v_add_u32_e32 v220, v220, v230
	v_or_b32_e32 v221, 16, v231
	v_xor_b32_e32 v221, v221, v232
	v_add_u32_e32 v221, v221, v230
	v_or_b32_e32 v222, 32, v231
	v_xor_b32_e32 v222, v222, v232
	v_add_u32_e32 v222, v222, v230
	v_or_b32_e32 v223, 48, v231
	v_xor_b32_e32 v223, v223, v232
	v_add_u32_e32 v223, v223, v230
	s_branch .LBB0_596

; #define LAS __attribute__((address_space(3)))
; #define MFMA16(a, b, c) __builtin_amdgcn_mfma_f32_16x16x32_bf16((a), (b), (c), 0, 0, 0)
; template <int DIR>
; __device__ __forceinline__ void rnn_scan_unit(const Params& p, LAS unsigned char* lds, int b, int g) {
;     ...
;           for (int n = 0; n < 4; ++n) { const int c4 = 16 * n + 4 * fq;
;               f32x4 ra = *(const LAS f32x4*)(cst + c4), ia = *(const LAS f32x4*)(cst + 64 + c4);
; #pragma unroll
;               for (int ks = 0; ks < 2; ++ks) { ra = MFMA16(wreg[(0 * 4 + n) * 2 + ks], af[ks], ra); ia = MFMA16(wl[((1 * 4 + n) * 2 + ks) * 64 + lane], af[ks], ia); }
;               const f32x4 xv = *(const LAS f32x4*)(xcf + tt * XS + c4);
;               const f32x4 spv = *(const LAS f32x4*)(cst + 128 + c4);
;               f32x4 av, bv;
; #pragma unroll
;               for (int i = 0; i < 4; ++i) { const float r = __builtin_amdgcn_rcpf(1.0f + __builtin_amdgcn_exp2f(ra[i])), ig = __builtin_amdgcn_rcpf(1.0f + __builtin_amdgcn_exp2f(ia[i]));
;                   const float a = __builtin_amdgcn_exp2f(r * spv[i]); const float em = fmaf(-a, a, 1.0f);
;                   av[i] = valid ? a : 1.0f; bv[i] = valid ? __builtin_amdgcn_sqrtf(fmaxf(em, 0.0f)) * ig * xv[i] : 0.0f; }
;               *(LAS f32x4*)(al + tt * 64 + c4) = av; *(LAS f32x4*)(bl + tt * 64 + c4) = bv; } }
.Lgate_nomask_3:
	ds_write_b128 v224, v[104:107] offset:6784
	ds_write_b128 v224, v[112:115] offset:10880
	ds_read_b128 v[96:99], v132
	ds_read_b128 v[100:103], v133
	ds_read_b128 v[104:107], v122 offset:10240
	s_waitcnt lgkmcnt(2)
	v_mfma_f32_16x16x32_bf16 v[96:99], v[52:55], v[88:91], v[96:99]
	v_mov_b32_e32 v113, 0
	v_mov_b32_e32 v112, 0
	s_waitcnt lgkmcnt(0)
	v_mfma_f32_16x16x32_bf16 v[100:103], v[104:107], v[88:91], v[100:103]
	v_mfma_f32_16x16x32_bf16 v[104:107], v[56:59], v[92:95], v[96:99]
	s_nop 2
	ds_read_b128 v[96:99], v122 offset:11264
	s_waitcnt lgkmcnt(0)
	v_mfma_f32_16x16x32_bf16 v[96:99], v[96:99], v[92:95], v[100:103]
	s_nop 1
	ds_read_b128 v[100:103], v129 offset:2496
	ds_read_b128 v[108:111], v134
	v_exp_f32_e32 v104, v104
	v_exp_f32_e32 v105, v105
	v_exp_f32_e32 v106, v106
	v_exp_f32_e32 v107, v107
	v_exp_f32_e32 v96, v96
	v_exp_f32_e32 v97, v97
	v_exp_f32_e32 v98, v98
	v_exp_f32_e32 v99, v99
	v_add_f32_e32 v104, 1.0, v104
	v_add_f32_e32 v105, 1.0, v105
	v_add_f32_e32 v106, 1.0, v106
	v_add_f32_e32 v107, 1.0, v107
	v_add_f32_e32 v96, 1.0, v96
	v_add_f32_e32 v97, 1.0, v97
	v_add_f32_e32 v98, 1.0, v98
	v_add_f32_e32 v99, 1.0, v99
	v_rcp_f32_e32 v104, v104
	v_rcp_f32_e32 v105, v105
	v_rcp_f32_e32 v106, v106
	v_rcp_f32_e32 v107, v107
	v_rcp_f32_e32 v96, v96
	v_rcp_f32_e32 v97, v97
	v_rcp_f32_e32 v98, v98
	v_rcp_f32_e32 v99, v99
	s_waitcnt lgkmcnt(0)
	v_mul_f32_e32 v104, v104, v108
	v_mul_f32_e32 v105, v105, v109
	v_mul_f32_e32 v106, v106, v110
	v_mul_f32_e32 v107, v107, v111
	v_exp_f32_e32 v104, v104
	v_exp_f32_e32 v105, v105
	v_exp_f32_e32 v106, v106
	v_exp_f32_e32 v107, v107
	v_fma_f32 v112, -v104, v104, 1.0
	v_fma_f32 v113, -v105, v105, 1.0
	v_fma_f32 v114, -v106, v106, 1.0
	v_fma_f32 v115, -v107, v107, 1.0
	v_max_f32_e32 v112, 0, v112
	v_max_f32_e32 v113, 0, v113
	v_max_f32_e32 v114, 0, v114
	v_max_f32_e32 v115, 0, v115
	v_sqrt_f32_e32 v112, v112
	v_sqrt_f32_e32 v113, v113
	v_sqrt_f32_e32 v114, v114
	v_sqrt_f32_e32 v115, v115
	v_mul_f32_e32 v96, v96, v112
	v_mul_f32_e32 v97, v97, v113
	v_mul_f32_e32 v98, v98, v114
	v_mul_f32_e32 v99, v99, v115
	v_mul_f32_e32 v112, v100, v96
	v_mul_f32_e32 v113, v101, v97
	v_mul_f32_e32 v114, v102, v98
	v_mul_f32_e32 v115, v103, v99
	s_cmp_eq_u64 s[16:17], exec
	s_cbranch_scc1 .Lgate_nomask_2
	v_cndmask_b32_e64 v112, 0, v112, s[16:17]
	v_cndmask_b32_e64 v113, 0, v113, s[16:17]
	v_cndmask_b32_e64 v114, 0, v114, s[16:17]
	v_cndmask_b32_e64 v115, 0, v115, s[16:17]
	v_cndmask_b32_e64 v104, 1.0, v104, s[16:17]
	v_cndmask_b32_e64 v105, 1.0, v105, s[16:17]
	v_cndmask_b32_e64 v106, 1.0, v106, s[16:17]
	v_cndmask_b32_e64 v107, 1.0, v107, s[16:17]
.Lgate_nomask_2:
	ds_write_b128 v225, v[104:107] offset:6784
	ds_write_b128 v225, v[112:115] offset:10880
	ds_read_b128 v[96:99], v135
	ds_read_b128 v[100:103], v136
	ds_read_b128 v[104:107], v122 offset:12288
	s_waitcnt lgkmcnt(2)
	v_mfma_f32_16x16x32_bf16 v[96:99], v[60:63], v[88:91], v[96:99]
	v_mov_b32_e32 v113, 0
	v_mov_b32_e32 v112, 0
	s_waitcnt lgkmcnt(0)
	v_mfma_f32_16x16x32_bf16 v[100:103], v[104:107], v[88:91], v[100:103]
	v_mfma_f32_16x16x32_bf16 v[104:107], v[64:67], v[92:95], v[96:99]
	s_nop 2
	ds_read_b128 v[96:99], v122 offset:13312
	s_waitcnt lgkmcnt(0)
	v_mfma_f32_16x16x32_bf16 v[96:99], v[96:99], v[92:95], v[100:103]
	s_nop 1
	ds_read_b128 v[100:103], v129 offset:2560
	ds_read_b128 v[108:111], v137
	v_exp_f32_e32 v104, v104
	v_exp_f32_e32 v105, v105
	v_exp_f32_e32 v106, v106
	v_exp_f32_e32 v107, v107
	v_exp_f32_e32 v96, v96
	v_exp_f32_e32 v97, v97
	v_exp_f32_e32 v98, v98
	v_exp_f32_e32 v99, v99
	v_add_f32_e32 v104, 1.0, v104
	v_add_f32_e32 v105, 1.0, v105
	v_add_f32_e32 v106, 1.0, v106
	v_add_f32_e32 v107, 1.0, v107
	v_add_f32_e32 v96, 1.0, v96
	v_add_f32_e32 v97, 1.0, v97
	v_add_f32_e32 v98, 1.0, v98
	v_add_f32_e32 v99, 1.0, v99
	v_rcp_f32_e32 v104, v104
	v_rcp_f32_e32 v105, v105
	v_rcp_f32_e32 v106, v106
	v_rcp_f32_e32 v107, v107
	v_rcp_f32_e32 v96, v96
	v_rcp_f32_e32 v97, v97
	v_rcp_f32_e32 v98, v98
	v_rcp_f32_e32 v99, v99
	s_waitcnt lgkmcnt(0)
	v_mul_f32_e32 v104, v104, v108
	v_mul_f32_e32 v105, v105, v109
	v_mul_f32_e32 v106, v106, v110
	v_mul_f32_e32 v107, v107, v111
	v_exp_f32_e32 v104, v104
	v_exp_f32_e32 v105, v105
	v_exp_f32_e32 v106, v106
	v_exp_f32_e32 v107, v107
	v_fma_f32 v112, -v104, v104, 1.0
	v_fma_f32 v113, -v105, v105, 1.0
	v_fma_f32 v114, -v106, v106, 1.0
	v_fma_f32 v115, -v107, v107, 1.0
	v_max_f32_e32 v112, 0, v112
	v_max_f32_e32 v113, 0, v113
	v_max_f32_e32 v114, 0, v114
	v_max_f32_e32 v115, 0, v115
	v_sqrt_f32_e32 v112, v112
	v_sqrt_f32_e32 v113, v113
	v_sqrt_f32_e32 v114, v114
	v_sqrt_f32_e32 v115, v115
	v_mul_f32_e32 v96, v96, v112
	v_mul_f32_e32 v97, v97, v113
	v_mul_f32_e32 v98, v98, v114
	v_mul_f32_e32 v99, v99, v115
	v_mul_f32_e32 v112, v100, v96
	v_mul_f32_e32 v113, v101, v97
	v_mul_f32_e32 v114, v102, v98
	v_mul_f32_e32 v115, v103, v99
	s_cmp_eq_u64 s[16:17], exec
	s_cbranch_scc1 .Lgate_nomask_1
	v_cndmask_b32_e64 v112, 0, v112, s[16:17]
	v_cndmask_b32_e64 v113, 0, v113, s[16:17]
	v_cndmask_b32_e64 v114, 0, v114, s[16:17]
	v_cndmask_b32_e64 v115, 0, v115, s[16:17]
	v_cndmask_b32_e64 v104, 1.0, v104, s[16:17]
	v_cndmask_b32_e64 v105, 1.0, v105, s[16:17]
	v_cndmask_b32_e64 v106, 1.0, v106, s[16:17]
	v_cndmask_b32_e64 v107, 1.0, v107, s[16:17]
; #define LAS __attribute__((address_space(3)))
; #define MFMA16(a, b, c) __builtin_amdgcn_mfma_f32_16x16x32_bf16((a), (b), (c), 0, 0, 0)
; template <int DIR>
; __device__ __forceinline__ void rnn_scan_unit(const Params& p, LAS unsigned char* lds, int b, int g) {
;     ...
;           for (int n = 0; n < 4; ++n) { const int c4 = 16 * n + 4 * fq;
;               f32x4 ra = *(const LAS f32x4*)(cst + c4), ia = *(const LAS f32x4*)(cst + 64 + c4);
; #pragma unroll
;               for (int ks = 0; ks < 2; ++ks) { ra = MFMA16(wreg[(0 * 4 + n) * 2 + ks], af[ks], ra); ia = MFMA16(wl[((1 * 4 + n) * 2 + ks) * 64 + lane], af[ks], ia); }
;               const f32x4 xv = *(const LAS f32x4*)(xcf + tt * XS + c4);
;               const f32x4 spv = *(const LAS f32x4*)(cst + 128 + c4);
;               f32x4 av, bv;
; #pragma unroll
;               for (int i = 0; i < 4; ++i) { const float r = __builtin_amdgcn_rcpf(1.0f + __builtin_amdgcn_exp2f(ra[i])), ig = __builtin_amdgcn_rcpf(1.0f + __builtin_amdgcn_exp2f(ia[i]));
;                   const float a = __builtin_amdgcn_exp2f(r * spv[i]); const float em = fmaf(-a, a, 1.0f);
;                   av[i] = valid ? a : 1.0f; bv[i] = valid ? __builtin_amdgcn_sqrtf(fmaxf(em, 0.0f)) * ig * xv[i] : 0.0f; }
;               *(LAS f32x4*)(al + tt * 64 + c4) = av; *(LAS f32x4*)(bl + tt * 64 + c4) = bv; } }
.Lgate_nomask_1:
	ds_write_b128 v226, v[104:107] offset:6784
	ds_write_b128 v226, v[112:115] offset:10880
	ds_read_b128 v[96:99], v138
	ds_read_b128 v[100:103], v139
	ds_read_b128 v[104:107], v122 offset:14336
	s_waitcnt lgkmcnt(2)
	v_mfma_f32_16x16x32_bf16 v[96:99], v[68:71], v[88:91], v[96:99]
	s_waitcnt lgkmcnt(0)
	v_mfma_f32_16x16x32_bf16 v[88:91], v[104:107], v[88:91], v[100:103]
	v_mov_b32_e32 v105, 0
	s_nop 1
	ds_read_b128 v[100:103], v122 offset:15360
	v_mov_b32_e32 v104, 0
	v_mfma_f32_16x16x32_bf16 v[96:99], v[72:75], v[92:95], v[96:99]
	s_waitcnt lgkmcnt(0)
	v_mfma_f32_16x16x32_bf16 v[88:91], v[100:103], v[92:95], v[88:91]
	ds_read_b128 v[92:95], v129 offset:2624
	ds_read_b128 v[100:103], v154
	s_nop 3
	v_exp_f32_e32 v96, v96
	v_exp_f32_e32 v97, v97
	v_exp_f32_e32 v98, v98
	v_exp_f32_e32 v99, v99
	v_exp_f32_e32 v88, v88
	v_exp_f32_e32 v89, v89
	v_exp_f32_e32 v90, v90
	v_exp_f32_e32 v91, v91
	v_add_f32_e32 v96, 1.0, v96
	v_add_f32_e32 v97, 1.0, v97
	v_add_f32_e32 v98, 1.0, v98
	v_add_f32_e32 v99, 1.0, v99
	v_add_f32_e32 v88, 1.0, v88
	v_add_f32_e32 v89, 1.0, v89
	v_add_f32_e32 v90, 1.0, v90
	v_add_f32_e32 v91, 1.0, v91
	v_rcp_f32_e32 v96, v96
	v_rcp_f32_e32 v97, v97
	v_rcp_f32_e32 v98, v98
	v_rcp_f32_e32 v99, v99
	v_rcp_f32_e32 v88, v88
	v_rcp_f32_e32 v89, v89
	v_rcp_f32_e32 v90, v90
	v_rcp_f32_e32 v91, v91
	s_waitcnt lgkmcnt(0)
	v_mul_f32_e32 v96, v96, v100
	v_mul_f32_e32 v97, v97, v101
	v_mul_f32_e32 v98, v98, v102
	v_mul_f32_e32 v99, v99, v103
	v_exp_f32_e32 v96, v96
	v_exp_f32_e32 v97, v97
	v_exp_f32_e32 v98, v98
	v_exp_f32_e32 v99, v99
	v_fma_f32 v104, -v96, v96, 1.0
	v_fma_f32 v105, -v97, v97, 1.0
	v_fma_f32 v106, -v98, v98, 1.0
	v_fma_f32 v107, -v99, v99, 1.0
	v_max_f32_e32 v104, 0, v104
	v_max_f32_e32 v105, 0, v105
	v_max_f32_e32 v106, 0, v106
	v_max_f32_e32 v107, 0, v107
	v_sqrt_f32_e32 v104, v104
	v_sqrt_f32_e32 v105, v105
	v_sqrt_f32_e32 v106, v106
	v_sqrt_f32_e32 v107, v107
	v_mul_f32_e32 v88, v88, v104
	v_mul_f32_e32 v89, v89, v105
	v_mul_f32_e32 v90, v90, v106
	v_mul_f32_e32 v91, v91, v107
	v_mul_f32_e32 v104, v92, v88
	v_mul_f32_e32 v105, v93, v89
	v_mul_f32_e32 v106, v94, v90
	v_mul_f32_e32 v107, v95, v91
	s_cmp_eq_u64 s[16:17], exec
	s_cbranch_scc1 .Lgate_nomask_0
	v_cndmask_b32_e64 v104, 0, v104, s[16:17]
	v_cndmask_b32_e64 v105, 0, v105, s[16:17]
	v_cndmask_b32_e64 v106, 0, v106, s[16:17]
	v_cndmask_b32_e64 v107, 0, v107, s[16:17]
	v_cndmask_b32_e64 v96, 1.0, v96, s[16:17]
	v_cndmask_b32_e64 v97, 1.0, v97, s[16:17]
	v_cndmask_b32_e64 v98, 1.0, v98, s[16:17]
	v_cndmask_b32_e64 v99, 1.0, v99, s[16:17]
; #define LAS __attribute__((address_space(3)))
; __device__ __forceinline__ unsigned cvt_pk(float lo, float hi) { unsigned r; asm("v_cvt_pk_bf16_f32 %0, %1, %2" : "=v"(r) : "v"(lo), "v"(hi)); return r; }
; #define LDS_BARRIER() asm volatile("s_waitcnt lgkmcnt(0)\n\ts_barrier" ::: "memory")
; template <int DIR>
; __device__ __forceinline__ void rnn_scan_unit(const Params& p, LAS unsigned char* lds, int b, int g) {
;     ...
;               *(LAS f32x4*)(al + tt * 64 + c4) = av; *(LAS f32x4*)(bl + tt * 64 + c4) = bv; } }
;         asm volatile("s_waitcnt lgkmcnt(0)" ::: "memory");
;         LAS float* sgA = sg + (ci & 1) * 1024; LAS float* sgB = sgA + 512;
;         float av_[16], bv_[16];
;         { float A = 1.f, B = 0.f;
; #pragma unroll
;           for (int k = 0; k < 16; ++k) { const int tt = DIR == 0 ? k : 15 - k; av_[k] = al[tt * 64 + ch]; bv_[k] = bl[tt * 64 + ch]; B = av_[k] * B + bv_[k]; A *= av_[k]; }
;           sgA[seg * 64 + ch] = A; sgB[seg * 64 + ch] = B; }
;         LDS_BARRIER();
;         float h = hcar, hin = hcar;
; #pragma unroll
;         for (int s = 0; s < 8; ++s) { const int sx = DIR == 0 ? s : 7 - s; hin = (sx == seg) ? h : hin; h = sgA[sx * 64 + ch] * h + sgB[sx * 64 + ch]; }
;         hcar = h;
; #pragma unroll
;         for (int k = 0; k < 16; ++k) { const int tt = DIR == 0 ? k : 15 - k; hin = av_[k] * hin + bv_[k]; bl[tt * 64 + ch] = hin; }
;         asm volatile("s_waitcnt lgkmcnt(0)" ::: "memory");
;         { const int tk = lane >> 2, cq4 = lane & 3;
;           if (t0 + tk < TT) { const LAS float* src = bl + tk * 64 + 16 * cq4;
;               const f32x4 x0 = *(const LAS f32x4*)(src), x1 = *(const LAS f32x4*)(src + 4), x2 = *(const LAS f32x4*)(src + 8), x3 = *(const LAS f32x4*)(src + 12);
;               u32x4 w0, w1; w0.x = cvt_pk(x0[0], x0[1]); w0.y = cvt_pk(x0[2], x0[3]); w0.z = cvt_pk(x1[0], x1[1]); w0.w = cvt_pk(x1[2], x1[3]);
;               w1.x = cvt_pk(x2[0], x2[1]); w1.y = cvt_pk(x2[2], x2[3]); w1.z = cvt_pk(x3[0], x3[1]); w1.w = cvt_pk(x3[2], x3[3]);
;               bf16_t* hp = H + ((size_t)b * TT + t0 + tk) * 512 + 64 * g + 16 * cq4;
;               *(u32x4*)hp = w0; *(u32x4*)(hp + 8) = w1; } }
.Lgate_nomask_0:
	ds_write_b128 v227, v[96:99] offset:6784
	ds_write_b128 v227, v[104:107] offset:10880
	s_waitcnt lgkmcnt(0)
	ds_read2st64_b32 v[180:181], v212 offset0:26 offset1:34
	ds_read2st64_b32 v[196:197], v212 offset0:42 offset1:50
	ds_read2st64_b32 v[182:183], v213 offset0:27 offset1:35
	ds_read2st64_b32 v[198:199], v213 offset0:43 offset1:51
	ds_read2st64_b32 v[184:185], v214 offset0:28 offset1:36
	ds_read2st64_b32 v[200:201], v214 offset0:44 offset1:52
	ds_read2st64_b32 v[186:187], v215 offset0:29 offset1:37
	ds_read2st64_b32 v[202:203], v215 offset0:45 offset1:53
	ds_read2st64_b32 v[188:189], v216 offset0:30 offset1:38
	ds_read2st64_b32 v[204:205], v216 offset0:46 offset1:54
	ds_read2st64_b32 v[190:191], v217 offset0:31 offset1:39
	ds_read2st64_b32 v[206:207], v217 offset0:47 offset1:55
	ds_read2st64_b32 v[192:193], v218 offset0:32 offset1:40
	ds_read2st64_b32 v[208:209], v218 offset0:48 offset1:56
	ds_read2st64_b32 v[194:195], v219 offset0:33 offset1:41
	ds_read2st64_b32 v[210:211], v219 offset0:49 offset1:57
	s_and_b32 s16, s34, 0x400
	s_lshl_b32 s16, s16, 2
	s_add_i32 s16, s16, 0
	s_add_i32 s16, s16, 0x1d400
	v_lshl_add_u32 v112, v120, 2, s16
	s_waitcnt lgkmcnt(14)
	v_fma_f32 v0, 0, v180, v196
	s_waitcnt lgkmcnt(12)
	v_fma_f32 v0, v0, v182, v198
	v_mul_f32_e32 v2, v180, v182
	s_waitcnt lgkmcnt(10)
	v_fma_f32 v0, v0, v184, v200
	v_mul_f32_e32 v2, v2, v184
	s_waitcnt lgkmcnt(8)
	v_fma_f32 v0, v0, v186, v202
	v_mul_f32_e32 v2, v2, v186
	s_waitcnt lgkmcnt(6)
	v_fma_f32 v0, v0, v188, v204
	v_mul_f32_e32 v2, v2, v188
	s_waitcnt lgkmcnt(4)
	v_fma_f32 v0, v0, v190, v206
	v_mul_f32_e32 v2, v2, v190
	s_waitcnt lgkmcnt(2)
	v_fma_f32 v0, v0, v192, v208
	v_mul_f32_e32 v2, v2, v192
	s_waitcnt lgkmcnt(0)
	v_fma_f32 v0, v0, v194, v210
	v_mul_f32_e32 v2, v2, v194
	v_fma_f32 v0, v0, v181, v197
	v_mul_f32_e32 v2, v2, v181
	v_fma_f32 v0, v0, v183, v199
	v_mul_f32_e32 v2, v2, v183
	v_fma_f32 v0, v0, v185, v201
	v_mul_f32_e32 v2, v2, v185
	v_fma_f32 v0, v0, v187, v203
	v_mul_f32_e32 v2, v2, v187
	v_fma_f32 v0, v0, v189, v205
	v_mul_f32_e32 v2, v2, v189
	v_fma_f32 v0, v0, v191, v207
	v_mul_f32_e32 v2, v2, v191
	v_fma_f32 v0, v0, v193, v209
	v_mul_f32_e32 v2, v2, v193
	v_fma_f32 v0, v0, v195, v211
	v_mul_f32_e32 v2, v2, v195
	ds_write2st64_b32 v112, v2, v0 offset1:8
	s_waitcnt lgkmcnt(0)
	s_barrier
	v_lshl_add_u32 v0, v121, 2, s16
	ds_read2st64_b32 v[112:113], v0 offset1:1
	ds_read2st64_b32 v[174:175], v0 offset0:8 offset1:9
	s_waitcnt lgkmcnt(0)
	v_fma_f32 v2, v3, v112, v174
	v_cndmask_b32_e64 v3, v3, v2, s[0:1]
	v_fmac_f32_e32 v175, v2, v113
	v_cndmask_b32_e64 v174, v3, v175, s[2:3]
	ds_read2st64_b32 v[2:3], v0 offset0:2 offset1:3
	ds_read2st64_b32 v[112:113], v0 offset0:10 offset1:11
	s_waitcnt lgkmcnt(0)
	v_fma_f32 v2, v175, v2, v112
	v_cndmask_b32_e64 v112, v174, v2, s[4:5]
	v_fmac_f32_e32 v113, v2, v3
	ds_read2st64_b32 v[2:3], v0 offset0:4 offset1:5
	ds_read2st64_b32 v[174:175], v0 offset0:12 offset1:13
	v_cndmask_b32_e64 v112, v112, v113, s[8:9]
	s_waitcnt lgkmcnt(0)
	v_fma_f32 v2, v113, v2, v174
	v_cndmask_b32_e64 v112, v112, v2, s[10:11]
	v_fmac_f32_e32 v175, v2, v3
	v_cndmask_b32_e64 v174, v112, v175, s[12:13]
	ds_read2st64_b32 v[112:113], v0 offset0:6 offset1:7
	ds_read2st64_b32 v[2:3], v0 offset0:14 offset1:15
	s_waitcnt lgkmcnt(0)
	v_fma_f32 v0, v175, v112, v2
	v_cndmask_b32_e64 v2, v174, v0, s[14:15]
	v_fma_f32 v196, v180, v2, v196
	v_fma_f32 v198, v182, v196, v198
	v_fma_f32 v200, v184, v198, v200
	v_fma_f32 v202, v186, v200, v202
	v_fma_f32 v204, v188, v202, v204
	v_fma_f32 v206, v190, v204, v206
	v_fma_f32 v208, v192, v206, v208
	v_fma_f32 v210, v194, v208, v210
	v_fma_f32 v197, v181, v210, v197
	ds_write2st64_b32 v212, v196, v197 offset0:42 offset1:50
	v_fma_f32 v199, v183, v197, v199
	ds_write2st64_b32 v213, v198, v199 offset0:43 offset1:51
	v_fma_f32 v201, v185, v199, v201
	ds_write2st64_b32 v214, v200, v201 offset0:44 offset1:52
	v_fma_f32 v203, v187, v201, v203
	ds_write2st64_b32 v215, v202, v203 offset0:45 offset1:53
	v_fma_f32 v205, v189, v203, v205
	ds_write2st64_b32 v216, v204, v205 offset0:46 offset1:54
	v_fma_f32 v207, v191, v205, v207
	ds_write2st64_b32 v217, v206, v207 offset0:47 offset1:55
	v_fma_f32 v209, v193, v207, v209
	ds_write2st64_b32 v218, v208, v209 offset0:48 offset1:56
	v_fma_f32 v211, v195, v209, v211
	ds_write2st64_b32 v219, v210, v211 offset0:49 offset1:57
	s_waitcnt lgkmcnt(0)
	v_add_u32_e32 v2, s19, v158
	v_cmp_gt_i32_e64 s[16:17], s86, v2
	s_waitcnt vmcnt(0)
	s_and_saveexec_b64 s[76:77], s[16:17]
	s_cbranch_execz .LBB0_595
	ds_read_b128 v[88:91], v220 offset:10880
	ds_read_b128 v[92:95], v221 offset:10880
	ds_read_b128 v[96:99], v222 offset:10880
	ds_read_b128 v[100:103], v223 offset:10880
	s_waitcnt lgkmcnt(3)
	v_cvt_pk_bf16_f32 v88, v88, v89
	v_cvt_pk_bf16_f32 v89, v90, v91
	s_waitcnt lgkmcnt(2)
	v_cvt_pk_bf16_f32 v90, v92, v93
	v_cvt_pk_bf16_f32 v91, v94, v95
	s_waitcnt lgkmcnt(1)
	v_cvt_pk_bf16_f32 v92, v96, v97
	v_cvt_pk_bf16_f32 v93, v98, v99
	s_waitcnt lgkmcnt(0)
	v_cvt_pk_bf16_f32 v94, v100, v101
	v_cvt_pk_bf16_f32 v95, v102, v103
	global_store_dwordx4 v[118:119], v[88:91], off
	global_store_dwordx4 v[118:119], v[92:95], off offset:16
	s_branch .LBB0_595
